# w3 + one load of all eight per-XCD queue heads before stealing (skips failed atomics on empty queues)
# baseline (speedup 1.0000x reference)
.Lq_try:
	s_add_i32 s24, s22, s23
	s_and_b32 s24, s24, 7
	s_cmp_eq_u32 s23, 0
	s_cbranch_scc1 .Lq_do
	s_cmp_eq_u32 s23, 1
	s_cbranch_scc0 .Lq_nopeek
	s_mov_b64 s[28:29], exec
	s_mov_b64 exec, 0xff
	v_mbcnt_lo_u32_b32 v223, -1, 0
	v_lshlrev_b32_e32 v223, 10, v223
	v_add_u32_e32 v223, 0x2000, v223
	global_load_dword v224, v223, s[16:17] sc1
	s_waitcnt vmcnt(0)
	v_cmp_gt_u32_e32 vcc, 0x78, v224
	s_nop 1
	s_mov_b32 s26, vcc_lo
	s_mov_b64 exec, s[28:29]
.Lq_nopeek:
	s_bitcmp1_b32 s26, s24
	s_cbranch_scc0 .Lq_next
.Lq_do:
	s_lshl_b32 s25, s24, 10
	s_add_i32 s25, s25, 0x2000
	v_mov_b32_e32 v0, s25
	v_mov_b32_e32 v2, 1
	global_atomic_add v2, v0, v2, s[16:17] sc0
	s_waitcnt vmcnt(0)
	v_readfirstlane_b32 s0, v2
	s_nop 3
	s_cmpk_lt_u32 s0, 0x78
	s_cbranch_scc1 .Lq_got
.Lq_next:
	s_add_i32 s23, s23, 1
	s_cmpk_lt_u32 s23, 8
	s_cbranch_scc1 .Lq_try
	v_mov_b32_e32 v2, 1
	global_atomic_add v2, v1, v2, s[16:17] sc0
	s_waitcnt vmcnt(0)
	v_readfirstlane_b32 s0, v2
	s_nop 3
	s_add_i32 s24, s0, 0x3c0
	s_cmpk_lt_u32 s0, 0x80
	s_cselect_b32 s0, s24, -1
	v_mov_b32_e32 v0, s0
	s_branch .LBB0_1306
